# MLA hand loop LDS fragment prefetch distance 6 (was 5); otherwise v136
# baseline (speedup 1.0000x reference)
.Lmf_loop:
	ds_read_b128 v[162:165], v216 offset:13312
	ds_read_b128 v[166:169], v216 offset:19968
	ds_read_b128 v[172:175], v216 offset:13344
	ds_read_b128 v[176:179], v216 offset:20000
	ds_read_b128 v[180:183], v216 offset:13376
	ds_read_b128 v[184:187], v216 offset:20032
	global_load_dwordx4 v[130:133], v235, s[14:15]
	global_load_dwordx4 v[134:137], v236, s[14:15]
	s_add_u32 s14, s14, 0x18000
	s_addc_u32 s15, s15, 0
	global_load_dwordx4 v[142:145], v237, s[12:13]
	s_add_u32 s12, s12, 0x80
	s_addc_u32 s13, s13, 0
	s_waitcnt lgkmcnt(5)
	v_mfma_f32_32x32x16_bf16 v[34:49], v[162:165], v[98:101], v[146:161]
	ds_read_b128 v[188:191], v216 offset:13408
	v_exp_f32_e32 v66, v66
	v_exp_f32_e32 v67, v67
	v_exp_f32_e32 v68, v68
	v_exp_f32_e32 v69, v69
	s_waitcnt lgkmcnt(5)
	v_mfma_f32_32x32x16_bf16 v[50:65], v[166:169], v[98:101], v[146:161]
	ds_read_b128 v[192:195], v216 offset:20064
	v_add_f32_e32 v171, v66, v171
	v_exp_f32_e32 v70, v70
	v_exp_f32_e32 v71, v71
	v_add_f32_e32 v171, v68, v171
	s_waitcnt lgkmcnt(5)
	v_mfma_f32_32x32x16_bf16 v[34:49], v[172:175], v[102:105], v[34:49]
	ds_read_b128 v[162:165], v216 offset:13440
	v_exp_f32_e32 v72, v72
	v_add_f32_e32 v197, v67, v69
	v_exp_f32_e32 v73, v73
	v_add_f32_e32 v171, v70, v171
	s_waitcnt lgkmcnt(5)
	v_mfma_f32_32x32x16_bf16 v[50:65], v[176:179], v[102:105], v[50:65]
	ds_read_b128 v[166:169], v216 offset:20096
	v_add_f32_e32 v197, v71, v197
	v_cvt_pk_bf16_f32 v66, v66, v67
	v_add_f32_e32 v171, v72, v171
	v_cvt_pk_bf16_f32 v67, v68, v69
	v_add_f32_e32 v197, v73, v197
	v_cvt_pk_bf16_f32 v68, v70, v71
	v_cvt_pk_bf16_f32 v69, v72, v73
	s_waitcnt lgkmcnt(5)
	v_mfma_f32_32x32x16_bf16 v[34:49], v[180:183], v[106:109], v[34:49]
	ds_read_b128 v[172:175], v216 offset:13472
	v_exp_f32_e32 v74, v74
	v_exp_f32_e32 v75, v75
	v_exp_f32_e32 v76, v76
	s_waitcnt lgkmcnt(5)
	v_mfma_f32_32x32x16_bf16 v[50:65], v[184:187], v[106:109], v[50:65]
	ds_read_b128 v[176:179], v216 offset:20128
	v_exp_f32_e32 v77, v77
	v_add_f32_e32 v171, v74, v171
	v_exp_f32_e32 v78, v78
	v_add_f32_e32 v197, v75, v197
	v_exp_f32_e32 v79, v79
	s_waitcnt lgkmcnt(5)
	v_mfma_f32_32x32x16_bf16 v[34:49], v[188:191], v[110:113], v[34:49]
	ds_read_b128 v[180:183], v217 offset:26624
	v_add_f32_e32 v171, v76, v171
	v_exp_f32_e32 v80, v80
	v_add_f32_e32 v197, v77, v197
	v_exp_f32_e32 v81, v81
	s_waitcnt lgkmcnt(5)
	v_mfma_f32_32x32x16_bf16 v[50:65], v[192:195], v[110:113], v[50:65]
	ds_read_b128 v[184:187], v217 offset:31232
	v_add_f32_e32 v171, v78, v171
	v_add_f32_e32 v197, v79, v197
	v_cvt_pk_bf16_f32 v74, v74, v75
	v_add_f32_e32 v171, v80, v171
	v_cvt_pk_bf16_f32 v75, v76, v77
	v_add_f32_e32 v197, v81, v197
	s_waitcnt lgkmcnt(5)
	v_mfma_f32_32x32x16_bf16 v[34:49], v[162:165], v[114:117], v[34:49]
	ds_read_b128 v[188:191], v217 offset:26656
	v_cvt_pk_bf16_f32 v76, v78, v79
	v_cvt_pk_bf16_f32 v77, v80, v81
	v_exp_f32_e32 v82, v82
	v_exp_f32_e32 v83, v83
	v_exp_f32_e32 v84, v84
	s_waitcnt lgkmcnt(5)
	v_mfma_f32_32x32x16_bf16 v[50:65], v[166:169], v[114:117], v[50:65]
	ds_read_b128 v[192:195], v217 offset:31264
	v_exp_f32_e32 v85, v85
	v_add_f32_e32 v171, v82, v171
	v_exp_f32_e32 v86, v86
	s_waitcnt lgkmcnt(5)
	v_mfma_f32_32x32x16_bf16 v[34:49], v[172:175], v[118:121], v[34:49]
	ds_read_b128 v[162:165], v217 offset:26688
	v_add_f32_e32 v197, v83, v197
	v_exp_f32_e32 v87, v87
	v_add_f32_e32 v171, v84, v171
	v_exp_f32_e32 v88, v88
	v_add_f32_e32 v197, v85, v197
	s_waitcnt lgkmcnt(5)
	v_mfma_f32_32x32x16_bf16 v[50:65], v[176:179], v[118:121], v[50:65]
	ds_read_b128 v[166:169], v217 offset:31296
	v_exp_f32_e32 v89, v89
	v_add_f32_e32 v171, v86, v171
	v_add_f32_e32 v197, v87, v197
	v_cvt_pk_bf16_f32 v82, v82, v83
	v_add_f32_e32 v171, v88, v171
	s_waitcnt lgkmcnt(5)
	v_mfma_f32_32x32x16_bf16 v[18:33], v[180:183], v[66:69], v[18:33]
	ds_read_b128 v[172:175], v217 offset:26720
	v_cvt_pk_bf16_f32 v83, v84, v85
	v_add_f32_e32 v197, v89, v197
	v_cvt_pk_bf16_f32 v84, v86, v87
	v_cvt_pk_bf16_f32 v85, v88, v89
	v_exp_f32_e32 v90, v90
	v_exp_f32_e32 v91, v91
	s_waitcnt lgkmcnt(5)
	v_mfma_f32_32x32x16_bf16 v[2:17], v[184:187], v[66:69], v[2:17]
	ds_read_b128 v[176:179], v217 offset:31328
	v_exp_f32_e32 v92, v92
	v_exp_f32_e32 v93, v93
	v_add_f32_e32 v171, v90, v171
	v_exp_f32_e32 v94, v94
	s_waitcnt lgkmcnt(5)
	v_mfma_f32_32x32x16_bf16 v[18:33], v[188:191], v[74:77], v[18:33]
	v_add_f32_e32 v197, v91, v197
	v_exp_f32_e32 v95, v95
	v_add_f32_e32 v171, v92, v171
	v_exp_f32_e32 v96, v96
	s_waitcnt lgkmcnt(4)
	v_mfma_f32_32x32x16_bf16 v[2:17], v[192:195], v[74:77], v[2:17]
	s_waitcnt vmcnt(3)
	v_add_u32_e32 v196, 0x8800, v215
	ds_write_b128 v228, v[122:125]
	ds_write_b128 v238, v[126:129]
	ds_write2_b64 v196, v[138:139], v[140:141] offset0:128 offset1:130
	v_add_f32_e32 v197, v93, v197
	v_exp_f32_e32 v97, v97
	v_add_f32_e32 v171, v94, v171
	v_add_f32_e32 v197, v95, v197
	v_cvt_pk_bf16_f32 v90, v90, v91
	s_waitcnt lgkmcnt(6)
	v_mfma_f32_32x32x16_bf16 v[18:33], v[162:165], v[82:85], v[18:33]
	v_add_f32_e32 v171, v96, v171
	v_cvt_pk_bf16_f32 v91, v92, v93
	v_add_f32_e32 v197, v97, v197
	v_cvt_pk_bf16_f32 v92, v94, v95
	v_cvt_pk_bf16_f32 v93, v96, v97
	v_max3_f32 v1, v34, v35, v36
	s_waitcnt lgkmcnt(5)
	v_mfma_f32_32x32x16_bf16 v[2:17], v[166:169], v[82:85], v[2:17]
	v_max3_f32 v170, v37, v38, v39
	v_max3_f32 v1, v1, v40, v41
	v_max3_f32 v170, v170, v42, v43
	v_max3_f32 v1, v1, v44, v45
	v_max3_f32 v170, v170, v46, v47
	v_max3_f32 v1, v1, v48, v49
	v_max3_f32 v170, v170, v50, v51
	s_waitcnt lgkmcnt(4)
	v_mfma_f32_32x32x16_bf16 v[18:33], v[172:175], v[90:93], v[18:33]
	v_max3_f32 v1, v1, v52, v53
	v_max3_f32 v170, v170, v54, v55
	v_max3_f32 v1, v1, v56, v57
	v_max3_f32 v170, v170, v58, v59
	v_max3_f32 v1, v1, v60, v61
	v_max3_f32 v170, v170, v62, v63
	s_waitcnt lgkmcnt(3)
	v_mfma_f32_32x32x16_bf16 v[2:17], v[176:179], v[90:93], v[2:17]
	v_max3_f32 v1, v1, v64, v65
	v_max_f32_e32 v1, v1, v170
	v_mov_b32_e32 v170, v1
	v_add_f32_e32 v171, v197, v171
	s_nop 0
	v_permlane32_swap_b32_e32 v1, v170
	v_max_f32_e32 v1, v1, v170
	v_cmp_lt_f32_e32 vcc, s93, v1
	s_cbranch_vccnz .Lmf_slow_0
.Lmf_join_0:
	s_waitcnt lgkmcnt(0)
	s_barrier
	ds_read_b128 v[162:165], v216 offset:0
	ds_read_b128 v[166:169], v216 offset:6656
	ds_read_b128 v[172:175], v216 offset:32
	ds_read_b128 v[176:179], v216 offset:6688
	ds_read_b128 v[180:183], v216 offset:64
	ds_read_b128 v[184:187], v216 offset:6720
	global_load_dwordx4 v[122:125], v235, s[14:15]
	global_load_dwordx4 v[126:129], v236, s[14:15]
	s_add_u32 s14, s14, 0x18000
	s_addc_u32 s15, s15, 0
	global_load_dwordx4 v[138:141], v237, s[12:13]
	s_add_u32 s12, s12, 0x80
	s_addc_u32 s13, s13, 0
	s_waitcnt lgkmcnt(5)
	v_mfma_f32_32x32x16_bf16 v[66:81], v[162:165], v[98:101], v[146:161]
	ds_read_b128 v[188:191], v216 offset:96
	v_exp_f32_e32 v34, v34
	v_exp_f32_e32 v35, v35
	v_exp_f32_e32 v36, v36
	v_exp_f32_e32 v37, v37
	s_waitcnt lgkmcnt(5)
	v_mfma_f32_32x32x16_bf16 v[82:97], v[166:169], v[98:101], v[146:161]
	ds_read_b128 v[192:195], v216 offset:6752
	v_add_f32_e32 v171, v34, v171
	v_exp_f32_e32 v38, v38
	v_exp_f32_e32 v39, v39
	v_add_f32_e32 v171, v36, v171
	s_waitcnt lgkmcnt(5)
	v_mfma_f32_32x32x16_bf16 v[66:81], v[172:175], v[102:105], v[66:81]
	ds_read_b128 v[162:165], v216 offset:128
	v_exp_f32_e32 v40, v40
	v_add_f32_e32 v197, v35, v37
	v_exp_f32_e32 v41, v41
	v_add_f32_e32 v171, v38, v171
	s_waitcnt lgkmcnt(5)
	v_mfma_f32_32x32x16_bf16 v[82:97], v[176:179], v[102:105], v[82:97]
	ds_read_b128 v[166:169], v216 offset:6784
	v_add_f32_e32 v197, v39, v197
	v_cvt_pk_bf16_f32 v34, v34, v35
	v_add_f32_e32 v171, v40, v171
	v_cvt_pk_bf16_f32 v35, v36, v37
	v_add_f32_e32 v197, v41, v197
	v_cvt_pk_bf16_f32 v36, v38, v39
	v_cvt_pk_bf16_f32 v37, v40, v41
	s_waitcnt lgkmcnt(5)
	v_mfma_f32_32x32x16_bf16 v[66:81], v[180:183], v[106:109], v[66:81]
	ds_read_b128 v[172:175], v216 offset:160
	v_exp_f32_e32 v42, v42
	v_exp_f32_e32 v43, v43
	v_exp_f32_e32 v44, v44
	s_waitcnt lgkmcnt(5)
	v_mfma_f32_32x32x16_bf16 v[82:97], v[184:187], v[106:109], v[82:97]
	ds_read_b128 v[176:179], v216 offset:6816
	v_exp_f32_e32 v45, v45
	v_add_f32_e32 v171, v42, v171
	v_exp_f32_e32 v46, v46
	v_add_f32_e32 v197, v43, v197
	v_exp_f32_e32 v47, v47
	s_waitcnt lgkmcnt(5)
	v_mfma_f32_32x32x16_bf16 v[66:81], v[188:191], v[110:113], v[66:81]
	ds_read_b128 v[180:183], v217 offset:35840
	v_add_f32_e32 v171, v44, v171
	v_exp_f32_e32 v48, v48
	v_add_f32_e32 v197, v45, v197
	v_exp_f32_e32 v49, v49
	s_waitcnt lgkmcnt(5)
	v_mfma_f32_32x32x16_bf16 v[82:97], v[192:195], v[110:113], v[82:97]
	ds_read_b128 v[184:187], v217 offset:40448
	v_add_f32_e32 v171, v46, v171
	v_add_f32_e32 v197, v47, v197
	v_cvt_pk_bf16_f32 v42, v42, v43
	v_add_f32_e32 v171, v48, v171
	v_cvt_pk_bf16_f32 v43, v44, v45
	v_add_f32_e32 v197, v49, v197
	s_waitcnt lgkmcnt(5)
	v_mfma_f32_32x32x16_bf16 v[66:81], v[162:165], v[114:117], v[66:81]
	ds_read_b128 v[188:191], v217 offset:35872
	v_cvt_pk_bf16_f32 v44, v46, v47
	v_cvt_pk_bf16_f32 v45, v48, v49
	v_exp_f32_e32 v50, v50
	v_exp_f32_e32 v51, v51
	v_exp_f32_e32 v52, v52
	s_waitcnt lgkmcnt(5)
	v_mfma_f32_32x32x16_bf16 v[82:97], v[166:169], v[114:117], v[82:97]
	ds_read_b128 v[192:195], v217 offset:40480
	v_exp_f32_e32 v53, v53
	v_add_f32_e32 v171, v50, v171
	v_exp_f32_e32 v54, v54
	s_waitcnt lgkmcnt(5)
	v_mfma_f32_32x32x16_bf16 v[66:81], v[172:175], v[118:121], v[66:81]
	ds_read_b128 v[162:165], v217 offset:35904
	v_add_f32_e32 v197, v51, v197
	v_exp_f32_e32 v55, v55
	v_add_f32_e32 v171, v52, v171
	v_exp_f32_e32 v56, v56
	v_add_f32_e32 v197, v53, v197
	s_waitcnt lgkmcnt(5)
	v_mfma_f32_32x32x16_bf16 v[82:97], v[176:179], v[118:121], v[82:97]
	ds_read_b128 v[166:169], v217 offset:40512
	v_exp_f32_e32 v57, v57
	v_add_f32_e32 v171, v54, v171
	v_add_f32_e32 v197, v55, v197
	v_cvt_pk_bf16_f32 v50, v50, v51
	v_add_f32_e32 v171, v56, v171
	s_waitcnt lgkmcnt(5)
	v_mfma_f32_32x32x16_bf16 v[18:33], v[180:183], v[34:37], v[18:33]
	ds_read_b128 v[172:175], v217 offset:35936
	v_cvt_pk_bf16_f32 v51, v52, v53
	v_add_f32_e32 v197, v57, v197
	v_cvt_pk_bf16_f32 v52, v54, v55
	v_cvt_pk_bf16_f32 v53, v56, v57
	v_exp_f32_e32 v58, v58
	v_exp_f32_e32 v59, v59
	s_waitcnt lgkmcnt(5)
	v_mfma_f32_32x32x16_bf16 v[2:17], v[184:187], v[34:37], v[2:17]
	ds_read_b128 v[176:179], v217 offset:40544
	v_exp_f32_e32 v60, v60
	v_exp_f32_e32 v61, v61
	v_add_f32_e32 v171, v58, v171
	v_exp_f32_e32 v62, v62
	s_waitcnt lgkmcnt(5)
	v_mfma_f32_32x32x16_bf16 v[18:33], v[188:191], v[42:45], v[18:33]
	v_add_f32_e32 v197, v59, v197
	v_exp_f32_e32 v63, v63
	v_add_f32_e32 v171, v60, v171
	v_exp_f32_e32 v64, v64
	s_waitcnt lgkmcnt(4)
	v_mfma_f32_32x32x16_bf16 v[2:17], v[192:195], v[42:45], v[2:17]
	s_waitcnt vmcnt(3)
	ds_write_b128 v228, v[130:133] offset:13312
	ds_write_b128 v238, v[134:137] offset:13312
	ds_write2_b64 v225, v[142:143], v[144:145] offset1:2
	v_add_f32_e32 v197, v61, v197
	v_exp_f32_e32 v65, v65
	v_add_f32_e32 v171, v62, v171
	v_add_f32_e32 v197, v63, v197
	v_cvt_pk_bf16_f32 v58, v58, v59
	s_waitcnt lgkmcnt(6)
	v_mfma_f32_32x32x16_bf16 v[18:33], v[162:165], v[50:53], v[18:33]
	v_add_f32_e32 v171, v64, v171
	v_cvt_pk_bf16_f32 v59, v60, v61
	v_add_f32_e32 v197, v65, v197
	v_cvt_pk_bf16_f32 v60, v62, v63
	v_cvt_pk_bf16_f32 v61, v64, v65
	v_max3_f32 v1, v66, v67, v68
	s_waitcnt lgkmcnt(5)
	v_mfma_f32_32x32x16_bf16 v[2:17], v[166:169], v[50:53], v[2:17]
	v_max3_f32 v170, v69, v70, v71
	v_max3_f32 v1, v1, v72, v73
	v_max3_f32 v170, v170, v74, v75
	v_max3_f32 v1, v1, v76, v77
	v_max3_f32 v170, v170, v78, v79
	v_max3_f32 v1, v1, v80, v81
	v_max3_f32 v170, v170, v82, v83
	s_waitcnt lgkmcnt(4)
	v_mfma_f32_32x32x16_bf16 v[18:33], v[172:175], v[58:61], v[18:33]
	v_max3_f32 v1, v1, v84, v85
	v_max3_f32 v170, v170, v86, v87
	v_max3_f32 v1, v1, v88, v89
	v_max3_f32 v170, v170, v90, v91
	v_max3_f32 v1, v1, v92, v93
	v_max3_f32 v170, v170, v94, v95
	s_waitcnt lgkmcnt(3)
	v_mfma_f32_32x32x16_bf16 v[2:17], v[176:179], v[58:61], v[2:17]
	v_max3_f32 v1, v1, v96, v97
	v_max_f32_e32 v1, v1, v170
	v_mov_b32_e32 v170, v1
	v_add_f32_e32 v171, v197, v171
	s_nop 0
	v_permlane32_swap_b32_e32 v1, v170
	v_max_f32_e32 v1, v1, v170
	v_cmp_lt_f32_e32 vcc, s93, v1
	s_cbranch_vccnz .Lmf_slow_1
